# fused final output stores without nt so L2 merges the interleaved 16-B pieces into full lines
# baseline (speedup 1.0000x reference)
; __device__ __forceinline__ float bf_lo(unsigned w) { return __uint_as_float(w << 16); }
; __device__ __forceinline__ float bf_hi(unsigned w) { return __uint_as_float(w & 0xffff0000u); }
; template <bool SRC_F32, int R> __device__ __forceinline__ void ew_load(EwSet<SRC_F32, R>& S, int rb, const float* hsrc32, const bf16* hsrcb, const bf16* f, const float* part, int lane) {
; #pragma unroll
;     for (int i = 0; i < R; ++i) S.p[i] = (lane < 16) ? part[(size_t)(rb + i) * 16 + lane] : 0.f;
; #pragma unroll
;     for (int i = 0; i < R; ++i)
; #pragma unroll
;         for (int j = 0; j < 4; ++j) {
;             S.fw[i][j] = ((const v2u*)(f + (size_t)(rb + i) * D) + lane)[64 * j];
;             if constexpr (SRC_F32) S.h32[i][j] = __builtin_nontemporal_load((const f32x4*)(hsrc32 + (size_t)(rb + i) * D) + lane + 64 * j);
;             else S.hb[i][j] = ((const v2u*)(hsrcb + (size_t)(rb + i) * D) + lane)[64 * j];
;         }
; }
; template <bool SRC_F32, bool FINAL, int R> __device__ __forceinline__ void ew_compute(const EwSet<SRC_F32, R>& S, int rb, const f32x4 (&g)[4], bf16* hb_out, float* out32, float scale, float* rs_out, int lane) {
; #pragma unroll
;     for (int i = 0; i < R; ++i) {
;         float q = S.p[i];
;         q += __shfl_xor(q, 1); q += __shfl_xor(q, 2); q += __shfl_xor(q, 4); q += __shfl_xor(q, 8);
;         const float ss = __shfl(q, 0);
;         const float rs = scale / sqrtf(ss * (1.f / D) + EPS);
;         float s2 = 0.f;
; #pragma unroll
;         for (int j = 0; j < 4; ++j) {
;             f32x4 h;
;             if constexpr (SRC_F32) h = S.h32[i][j];
;             else { const v2u hw = S.hb[i][j]; h.x = bf_lo(hw.x); h.y = bf_hi(hw.x); h.z = bf_lo(hw.y); h.w = bf_hi(hw.y); }
;             const v2u fw = S.fw[i][j];
;             f32x4 v; v.x = h.x + bf_lo(fw.x) * rs * g[j].x; v.y = h.y + bf_hi(fw.x) * rs * g[j].y; v.z = h.z + bf_lo(fw.y) * rs * g[j].z; v.w = h.w + bf_hi(fw.y) * rs * g[j].w;
;             if (FINAL) __builtin_nontemporal_store(v, (f32x4*)(out32 + (size_t)(rb + i) * D) + lane + 64 * j);
.Lp13_bskip:
	s_barrier
	v_lshl_add_u32 v165, v154, 6, v157
	global_load_dwordx4 v[196:199], v165, s[20:21]
	v_add_u32_e32 v163, 0x400, v165
	global_load_dwordx4 v[200:203], v163, s[20:21]
	v_add_u32_e32 v163, 0x800, v165
	global_load_dwordx4 v[204:207], v163, s[20:21]
	v_add_u32_e32 v163, 0xc00, v165
	global_load_dwordx4 v[208:211], v163, s[20:21]
	v_add_u32_e32 v163, 0x2000, v165
	global_load_dwordx4 v[212:215], v163, s[20:21]
	v_add_u32_e32 v163, 0x2400, v165
	global_load_dwordx4 v[216:219], v163, s[20:21]
	v_add_u32_e32 v163, 0x2800, v165
	global_load_dwordx4 v[220:223], v163, s[20:21]
	v_add_u32_e32 v163, 0x2c00, v165
	global_load_dwordx4 v[224:227], v163, s[20:21]
	s_waitcnt vmcnt(0)
	v_add_f32_e32 v128, v196, v197
	v_add_f32_e32 v128, v198, v128
	v_add_f32_e32 v128, v199, v128
	v_add_f32_e32 v129, v200, v201
	v_add_f32_e32 v129, v202, v129
	v_add_f32_e32 v129, v203, v129
	v_add_f32_e32 v130, v204, v205
	v_add_f32_e32 v130, v206, v130
	v_add_f32_e32 v130, v207, v130
	v_add_f32_e32 v131, v208, v209
	v_add_f32_e32 v131, v210, v131
	v_add_f32_e32 v131, v211, v131
	v_add_f32_e32 v132, v212, v213
	v_add_f32_e32 v132, v214, v132
	v_add_f32_e32 v132, v215, v132
	v_add_f32_e32 v133, v216, v217
	v_add_f32_e32 v133, v218, v133
	v_add_f32_e32 v133, v219, v133
	v_add_f32_e32 v134, v220, v221
	v_add_f32_e32 v134, v222, v134
	v_add_f32_e32 v134, v223, v134
	v_add_f32_e32 v135, v224, v225
	v_add_f32_e32 v135, v226, v135
	v_add_f32_e32 v135, v227, v135
	s_nop 1
	ds_bpermute_b32 v248, v177, v128
	ds_bpermute_b32 v249, v177, v129
	ds_bpermute_b32 v250, v177, v130
	ds_bpermute_b32 v251, v177, v131
	ds_bpermute_b32 v252, v177, v132
	ds_bpermute_b32 v253, v177, v133
	ds_bpermute_b32 v247, v177, v134
	ds_bpermute_b32 v245, v177, v135
	s_waitcnt lgkmcnt(0)
	v_add_f32_e32 v128, v128, v248
	v_add_f32_e32 v129, v129, v249
	v_add_f32_e32 v130, v130, v250
	v_add_f32_e32 v131, v131, v251
	v_add_f32_e32 v132, v132, v252
	v_add_f32_e32 v133, v133, v253
	v_add_f32_e32 v134, v134, v247
	v_add_f32_e32 v135, v135, v245
	s_nop 1
	ds_bpermute_b32 v248, v155, v128
	ds_bpermute_b32 v249, v155, v129
	ds_bpermute_b32 v250, v155, v130
	ds_bpermute_b32 v251, v155, v131
	ds_bpermute_b32 v252, v155, v132
	ds_bpermute_b32 v253, v155, v133
	ds_bpermute_b32 v247, v155, v134
	ds_bpermute_b32 v245, v155, v135
	s_waitcnt lgkmcnt(0)
	v_add_f32_e32 v128, v128, v248
	v_add_f32_e32 v129, v129, v249
	v_add_f32_e32 v130, v130, v250
	v_add_f32_e32 v131, v131, v251
	v_add_f32_e32 v132, v132, v252
	v_add_f32_e32 v133, v133, v253
	v_add_f32_e32 v134, v134, v247
	v_add_f32_e32 v135, v135, v245
	v_mul_f32_e32 v128, 0x3a800000, v128
	v_mul_f32_e32 v129, 0x3a800000, v129
	v_mul_f32_e32 v130, 0x3a800000, v130
	v_mul_f32_e32 v131, 0x3a800000, v131
	v_mul_f32_e32 v132, 0x3a800000, v132
	v_mul_f32_e32 v133, 0x3a800000, v133
	v_mul_f32_e32 v134, 0x3a800000, v134
	v_mul_f32_e32 v135, 0x3a800000, v135
	v_add_f32_e32 v128, 0x358637bd, v128
	v_add_f32_e32 v129, 0x358637bd, v129
	v_add_f32_e32 v130, 0x358637bd, v130
	v_add_f32_e32 v131, 0x358637bd, v131
	v_add_f32_e32 v132, 0x358637bd, v132
	v_add_f32_e32 v133, 0x358637bd, v133
	v_add_f32_e32 v134, 0x358637bd, v134
	v_add_f32_e32 v135, 0x358637bd, v135
	v_rsq_f32_e32 v158, v128
	v_rsq_f32_e32 v160, v129
	v_rsq_f32_e32 v162, v130
	v_rsq_f32_e32 v164, v131
	v_rsq_f32_e32 v166, v132
	v_rsq_f32_e32 v168, v133
	v_rsq_f32_e32 v244, v134
	v_rsq_f32_e32 v246, v135
	s_nop 0
	v_add_u32_e32 v159, 0x10000, v152
	global_load_dwordx4 v[196:199], v159, s[66:67]
	global_load_dwordx4 v[200:203], v159, s[66:67] offset:256
	v_add_u32_e32 v159, 0x18000, v152
	global_load_dwordx4 v[204:207], v159, s[66:67]
	global_load_dwordx4 v[208:211], v159, s[66:67] offset:256
	v_add_u32_e32 v159, 0x40000, v152
	global_load_dwordx4 v[212:215], v159, s[66:67]
	global_load_dwordx4 v[216:219], v159, s[66:67] offset:256
	v_add_u32_e32 v159, 0x48000, v152
	global_load_dwordx4 v[220:223], v159, s[66:67]
	global_load_dwordx4 v[224:227], v159, s[66:67] offset:256
	v_lshlrev_b32_e32 v248, 16, v178
	v_and_b32_e32 v249, 0xffff0000, v178
	v_pk_mul_f32 v[124:125], v[124:125], v[158:159] op_sel_hi:[1,0]
	v_pk_fma_f32 v[124:125], v[124:125], v[228:229], v[248:249]
	v_lshlrev_b32_e32 v250, 16, v179
	v_and_b32_e32 v251, 0xffff0000, v179
	v_pk_mul_f32 v[126:127], v[126:127], v[158:159] op_sel_hi:[1,0]
	v_pk_fma_f32 v[126:127], v[126:127], v[230:231], v[250:251]
	v_lshlrev_b32_e32 v252, 16, v180
	v_and_b32_e32 v253, 0xffff0000, v180
	v_pk_mul_f32 v[120:121], v[120:121], v[158:159] op_sel_hi:[1,0]
	v_pk_fma_f32 v[120:121], v[120:121], v[232:233], v[252:253]
	v_lshlrev_b32_e32 v248, 16, v181
	v_and_b32_e32 v249, 0xffff0000, v181
	v_pk_mul_f32 v[122:123], v[122:123], v[158:159] op_sel_hi:[1,0]
	v_pk_fma_f32 v[122:123], v[122:123], v[234:235], v[248:249]
	v_lshlrev_b32_e32 v250, 16, v182
	v_and_b32_e32 v251, 0xffff0000, v182
	v_pk_mul_f32 v[116:117], v[116:117], v[158:159] op_sel_hi:[1,0]
	v_pk_fma_f32 v[116:117], v[116:117], v[236:237], v[250:251]
	v_lshlrev_b32_e32 v252, 16, v183
	v_and_b32_e32 v253, 0xffff0000, v183
	v_pk_mul_f32 v[118:119], v[118:119], v[158:159] op_sel_hi:[1,0]
	v_pk_fma_f32 v[118:119], v[118:119], v[238:239], v[252:253]
	v_lshlrev_b32_e32 v248, 16, v184
	v_and_b32_e32 v249, 0xffff0000, v184
	v_pk_mul_f32 v[112:113], v[112:113], v[158:159] op_sel_hi:[1,0]
	v_pk_fma_f32 v[112:113], v[112:113], v[240:241], v[248:249]
	v_lshlrev_b32_e32 v250, 16, v185
	v_and_b32_e32 v251, 0xffff0000, v185
	v_pk_mul_f32 v[114:115], v[114:115], v[158:159] op_sel_hi:[1,0]
	v_pk_fma_f32 v[114:115], v[114:115], v[242:243], v[250:251]
	v_lshlrev_b32_e32 v161, 1, v152
	global_store_dwordx4 v161, v[124:127], s[64:65]
; __device__ __forceinline__ float bf_lo(unsigned w) { return __uint_as_float(w << 16); }
; __device__ __forceinline__ float bf_hi(unsigned w) { return __uint_as_float(w & 0xffff0000u); }
; template <bool SRC_F32, bool FINAL, int R> __device__ __forceinline__ void ew_compute(const EwSet<SRC_F32, R>& S, int rb, const f32x4 (&g)[4], bf16* hb_out, float* out32, float scale, float* rs_out, int lane) {
;     ...
; #pragma unroll
;         for (int j = 0; j < 4; ++j) {
;             f32x4 h;
;             if constexpr (SRC_F32) h = S.h32[i][j];
;             else { const v2u hw = S.hb[i][j]; h.x = bf_lo(hw.x); h.y = bf_hi(hw.x); h.z = bf_lo(hw.y); h.w = bf_hi(hw.y); }
;             const v2u fw = S.fw[i][j];
;             f32x4 v; v.x = h.x + bf_lo(fw.x) * rs * g[j].x; v.y = h.y + bf_hi(fw.x) * rs * g[j].y; v.z = h.z + bf_lo(fw.y) * rs * g[j].z; v.w = h.w + bf_hi(fw.y) * rs * g[j].w;
;             if (FINAL) __builtin_nontemporal_store(v, (f32x4*)(out32 + (size_t)(rb + i) * D) + lane + 64 * j);
	global_store_dwordx4 v161, v[120:123], s[64:65] offset:16
	global_store_dwordx4 v161, v[116:119], s[64:65] offset:512
	global_store_dwordx4 v161, v[112:115], s[64:65] offset:528
	v_lshlrev_b32_e32 v248, 16, v186
	v_and_b32_e32 v249, 0xffff0000, v186
	v_pk_mul_f32 v[108:109], v[108:109], v[160:161] op_sel_hi:[1,0]
	v_pk_fma_f32 v[108:109], v[108:109], v[228:229], v[248:249]
	v_lshlrev_b32_e32 v250, 16, v187
	v_and_b32_e32 v251, 0xffff0000, v187
	v_pk_mul_f32 v[110:111], v[110:111], v[160:161] op_sel_hi:[1,0]
	v_pk_fma_f32 v[110:111], v[110:111], v[230:231], v[250:251]
	v_lshlrev_b32_e32 v252, 16, v188
	v_and_b32_e32 v253, 0xffff0000, v188
	v_pk_mul_f32 v[104:105], v[104:105], v[160:161] op_sel_hi:[1,0]
	v_pk_fma_f32 v[104:105], v[104:105], v[232:233], v[252:253]
	v_lshlrev_b32_e32 v248, 16, v189
	v_and_b32_e32 v249, 0xffff0000, v189
	v_pk_mul_f32 v[106:107], v[106:107], v[160:161] op_sel_hi:[1,0]
	v_pk_fma_f32 v[106:107], v[106:107], v[234:235], v[248:249]
	v_lshlrev_b32_e32 v250, 16, v190
	v_and_b32_e32 v251, 0xffff0000, v190
	v_pk_mul_f32 v[100:101], v[100:101], v[160:161] op_sel_hi:[1,0]
	v_pk_fma_f32 v[100:101], v[100:101], v[236:237], v[250:251]
	v_lshlrev_b32_e32 v252, 16, v191
	v_and_b32_e32 v253, 0xffff0000, v191
	v_pk_mul_f32 v[102:103], v[102:103], v[160:161] op_sel_hi:[1,0]
	v_pk_fma_f32 v[102:103], v[102:103], v[238:239], v[252:253]
	v_lshlrev_b32_e32 v248, 16, v192
	v_and_b32_e32 v249, 0xffff0000, v192
	v_pk_mul_f32 v[96:97], v[96:97], v[160:161] op_sel_hi:[1,0]
	v_pk_fma_f32 v[96:97], v[96:97], v[240:241], v[248:249]
	v_lshlrev_b32_e32 v250, 16, v193
	v_and_b32_e32 v251, 0xffff0000, v193
	v_pk_mul_f32 v[98:99], v[98:99], v[160:161] op_sel_hi:[1,0]
	v_pk_fma_f32 v[98:99], v[98:99], v[242:243], v[250:251]
	v_add_u32_e32 v161, 0x8000, v152
	v_lshlrev_b32_e32 v161, 1, v161
	global_store_dwordx4 v161, v[108:111], s[64:65]
	global_store_dwordx4 v161, v[104:107], s[64:65] offset:16
	global_store_dwordx4 v161, v[100:103], s[64:65] offset:512
	global_store_dwordx4 v161, v[96:99], s[64:65] offset:528
	v_add_u32_e32 v159, 0x50000, v152
	global_load_dwordx4 v[178:181], v159, s[66:67]
	global_load_dwordx4 v[182:185], v159, s[66:67] offset:256
	v_add_u32_e32 v159, 0x58000, v152
	global_load_dwordx4 v[186:189], v159, s[66:67]
	global_load_dwordx4 v[190:193], v159, s[66:67] offset:256
	s_waitcnt vmcnt(18)
	v_lshlrev_b32_e32 v248, 16, v196
	v_and_b32_e32 v249, 0xffff0000, v196
	v_pk_mul_f32 v[92:93], v[92:93], v[162:163] op_sel_hi:[1,0]
	v_pk_fma_f32 v[92:93], v[92:93], v[228:229], v[248:249]
	v_lshlrev_b32_e32 v250, 16, v197
	v_and_b32_e32 v251, 0xffff0000, v197
	v_pk_mul_f32 v[94:95], v[94:95], v[162:163] op_sel_hi:[1,0]
	v_pk_fma_f32 v[94:95], v[94:95], v[230:231], v[250:251]
	v_lshlrev_b32_e32 v252, 16, v198
	v_and_b32_e32 v253, 0xffff0000, v198
	v_pk_mul_f32 v[88:89], v[88:89], v[162:163] op_sel_hi:[1,0]
	v_pk_fma_f32 v[88:89], v[88:89], v[232:233], v[252:253]
	v_lshlrev_b32_e32 v248, 16, v199
	v_and_b32_e32 v249, 0xffff0000, v199
	v_pk_mul_f32 v[90:91], v[90:91], v[162:163] op_sel_hi:[1,0]
	v_pk_fma_f32 v[90:91], v[90:91], v[234:235], v[248:249]
	v_lshlrev_b32_e32 v250, 16, v200
	v_and_b32_e32 v251, 0xffff0000, v200
	v_pk_mul_f32 v[84:85], v[84:85], v[162:163] op_sel_hi:[1,0]
	v_pk_fma_f32 v[84:85], v[84:85], v[236:237], v[250:251]
	v_lshlrev_b32_e32 v252, 16, v201
	v_and_b32_e32 v253, 0xffff0000, v201
	v_pk_mul_f32 v[86:87], v[86:87], v[162:163] op_sel_hi:[1,0]
	v_pk_fma_f32 v[86:87], v[86:87], v[238:239], v[252:253]
	v_lshlrev_b32_e32 v248, 16, v202
	v_and_b32_e32 v249, 0xffff0000, v202
	v_pk_mul_f32 v[80:81], v[80:81], v[162:163] op_sel_hi:[1,0]
	v_pk_fma_f32 v[80:81], v[80:81], v[240:241], v[248:249]
	v_lshlrev_b32_e32 v250, 16, v203
	v_and_b32_e32 v251, 0xffff0000, v203
	v_pk_mul_f32 v[82:83], v[82:83], v[162:163] op_sel_hi:[1,0]
	v_pk_fma_f32 v[82:83], v[82:83], v[242:243], v[250:251]
	v_add_u32_e32 v161, 0x10000, v152
	v_lshlrev_b32_e32 v161, 1, v161
	global_store_dwordx4 v161, v[92:95], s[64:65]
	global_store_dwordx4 v161, v[88:91], s[64:65] offset:16
	global_store_dwordx4 v161, v[84:87], s[64:65] offset:512
	global_store_dwordx4 v161, v[80:83], s[64:65] offset:528
	s_waitcnt vmcnt(20)
	v_lshlrev_b32_e32 v248, 16, v204
	v_and_b32_e32 v249, 0xffff0000, v204
	v_pk_mul_f32 v[76:77], v[76:77], v[164:165] op_sel_hi:[1,0]
	v_pk_fma_f32 v[76:77], v[76:77], v[228:229], v[248:249]
	v_lshlrev_b32_e32 v250, 16, v205
	v_and_b32_e32 v251, 0xffff0000, v205
	v_pk_mul_f32 v[78:79], v[78:79], v[164:165] op_sel_hi:[1,0]
	v_pk_fma_f32 v[78:79], v[78:79], v[230:231], v[250:251]
	v_lshlrev_b32_e32 v252, 16, v206
	v_and_b32_e32 v253, 0xffff0000, v206
	v_pk_mul_f32 v[72:73], v[72:73], v[164:165] op_sel_hi:[1,0]
	v_pk_fma_f32 v[72:73], v[72:73], v[232:233], v[252:253]
	v_lshlrev_b32_e32 v248, 16, v207
	v_and_b32_e32 v249, 0xffff0000, v207
	v_pk_mul_f32 v[74:75], v[74:75], v[164:165] op_sel_hi:[1,0]
	v_pk_fma_f32 v[74:75], v[74:75], v[234:235], v[248:249]
	v_lshlrev_b32_e32 v250, 16, v208
	v_and_b32_e32 v251, 0xffff0000, v208
	v_pk_mul_f32 v[68:69], v[68:69], v[164:165] op_sel_hi:[1,0]
	v_pk_fma_f32 v[68:69], v[68:69], v[236:237], v[250:251]
	v_lshlrev_b32_e32 v252, 16, v209
	v_and_b32_e32 v253, 0xffff0000, v209
	v_pk_mul_f32 v[70:71], v[70:71], v[164:165] op_sel_hi:[1,0]
	v_pk_fma_f32 v[70:71], v[70:71], v[238:239], v[252:253]
	v_lshlrev_b32_e32 v248, 16, v210
	v_and_b32_e32 v249, 0xffff0000, v210
	v_pk_mul_f32 v[64:65], v[64:65], v[164:165] op_sel_hi:[1,0]
	v_pk_fma_f32 v[64:65], v[64:65], v[240:241], v[248:249]
	v_lshlrev_b32_e32 v250, 16, v211
	v_and_b32_e32 v251, 0xffff0000, v211
	v_pk_mul_f32 v[66:67], v[66:67], v[164:165] op_sel_hi:[1,0]
	v_pk_fma_f32 v[66:67], v[66:67], v[242:243], v[250:251]
	v_add_u32_e32 v161, 0x18000, v152
	v_lshlrev_b32_e32 v161, 1, v161
	global_store_dwordx4 v161, v[76:79], s[64:65]
	global_store_dwordx4 v161, v[72:75], s[64:65] offset:16
	global_store_dwordx4 v161, v[68:71], s[64:65] offset:512
	global_store_dwordx4 v161, v[64:67], s[64:65] offset:528
	s_waitcnt vmcnt(22)
; __device__ __forceinline__ float bf_lo(unsigned w) { return __uint_as_float(w << 16); }
; __device__ __forceinline__ float bf_hi(unsigned w) { return __uint_as_float(w & 0xffff0000u); }
; __device__ __forceinline__ unsigned pk2(float lo, float hi) { bf16x2_t r = __builtin_convertvector((f32x2_t){lo, hi}, bf16x2_t); return __builtin_bit_cast(unsigned, r); }
; template <bool SRC_F32, bool FINAL, int R> __device__ __forceinline__ void ew_compute(const EwSet<SRC_F32, R>& S, int rb, const f32x4 (&g)[4], bf16* hb_out, float* out32, float scale, float* rs_out, int lane) {
;     ...
;             f32x4 h;
;             if constexpr (SRC_F32) h = S.h32[i][j];
;             else { const v2u hw = S.hb[i][j]; h.x = bf_lo(hw.x); h.y = bf_hi(hw.x); h.z = bf_lo(hw.y); h.w = bf_hi(hw.y); }
;             const v2u fw = S.fw[i][j];
;             f32x4 v; v.x = h.x + bf_lo(fw.x) * rs * g[j].x; v.y = h.y + bf_hi(fw.x) * rs * g[j].y; v.z = h.z + bf_lo(fw.y) * rs * g[j].z; v.w = h.w + bf_hi(fw.y) * rs * g[j].w;
;             if (FINAL) __builtin_nontemporal_store(v, (f32x4*)(out32 + (size_t)(rb + i) * D) + lane + 64 * j);
;             else { v2u o; o.x = pk2(v.x, v.y); o.y = pk2(v.z, v.w); ((v2u*)(hb_out + (size_t)(rb + i) * D) + lane)[64 * j] = o; s2 += (v.x * v.x + v.y * v.y) + (v.z * v.z + v.w * v.w); }
	v_lshlrev_b32_e32 v248, 16, v212
	v_and_b32_e32 v249, 0xffff0000, v212
	v_pk_mul_f32 v[60:61], v[60:61], v[166:167] op_sel_hi:[1,0]
	v_pk_fma_f32 v[60:61], v[60:61], v[228:229], v[248:249]
	v_lshlrev_b32_e32 v250, 16, v213
	v_and_b32_e32 v251, 0xffff0000, v213
	v_pk_mul_f32 v[62:63], v[62:63], v[166:167] op_sel_hi:[1,0]
	v_pk_fma_f32 v[62:63], v[62:63], v[230:231], v[250:251]
	v_lshlrev_b32_e32 v252, 16, v214
	v_and_b32_e32 v253, 0xffff0000, v214
	v_pk_mul_f32 v[56:57], v[56:57], v[166:167] op_sel_hi:[1,0]
	v_pk_fma_f32 v[56:57], v[56:57], v[232:233], v[252:253]
	v_lshlrev_b32_e32 v248, 16, v215
	v_and_b32_e32 v249, 0xffff0000, v215
	v_pk_mul_f32 v[58:59], v[58:59], v[166:167] op_sel_hi:[1,0]
	v_pk_fma_f32 v[58:59], v[58:59], v[234:235], v[248:249]
	v_lshlrev_b32_e32 v250, 16, v216
	v_and_b32_e32 v251, 0xffff0000, v216
	v_pk_mul_f32 v[52:53], v[52:53], v[166:167] op_sel_hi:[1,0]
	v_pk_fma_f32 v[52:53], v[52:53], v[236:237], v[250:251]
	v_lshlrev_b32_e32 v252, 16, v217
	v_and_b32_e32 v253, 0xffff0000, v217
	v_pk_mul_f32 v[54:55], v[54:55], v[166:167] op_sel_hi:[1,0]
	v_pk_fma_f32 v[54:55], v[54:55], v[238:239], v[252:253]
	v_lshlrev_b32_e32 v248, 16, v218
	v_and_b32_e32 v249, 0xffff0000, v218
	v_pk_mul_f32 v[48:49], v[48:49], v[166:167] op_sel_hi:[1,0]
	v_pk_fma_f32 v[48:49], v[48:49], v[240:241], v[248:249]
	v_lshlrev_b32_e32 v250, 16, v219
	v_and_b32_e32 v251, 0xffff0000, v219
	v_pk_mul_f32 v[50:51], v[50:51], v[166:167] op_sel_hi:[1,0]
	v_pk_fma_f32 v[50:51], v[50:51], v[242:243], v[250:251]
	v_add_u32_e32 v161, 0x40000, v152
	v_lshlrev_b32_e32 v161, 1, v161
	global_store_dwordx4 v161, v[60:63], s[64:65]
	global_store_dwordx4 v161, v[56:59], s[64:65] offset:16
	global_store_dwordx4 v161, v[52:55], s[64:65] offset:512
	global_store_dwordx4 v161, v[48:51], s[64:65] offset:528
	s_waitcnt vmcnt(24)
	v_lshlrev_b32_e32 v248, 16, v220
	v_and_b32_e32 v249, 0xffff0000, v220
	v_pk_mul_f32 v[44:45], v[44:45], v[168:169] op_sel_hi:[1,0]
	v_pk_fma_f32 v[44:45], v[44:45], v[228:229], v[248:249]
	v_lshlrev_b32_e32 v250, 16, v221
	v_and_b32_e32 v251, 0xffff0000, v221
	v_pk_mul_f32 v[46:47], v[46:47], v[168:169] op_sel_hi:[1,0]
	v_pk_fma_f32 v[46:47], v[46:47], v[230:231], v[250:251]
	v_lshlrev_b32_e32 v252, 16, v222
	v_and_b32_e32 v253, 0xffff0000, v222
	v_pk_mul_f32 v[40:41], v[40:41], v[168:169] op_sel_hi:[1,0]
	v_pk_fma_f32 v[40:41], v[40:41], v[232:233], v[252:253]
	v_lshlrev_b32_e32 v248, 16, v223
	v_and_b32_e32 v249, 0xffff0000, v223
	v_pk_mul_f32 v[42:43], v[42:43], v[168:169] op_sel_hi:[1,0]
	v_pk_fma_f32 v[42:43], v[42:43], v[234:235], v[248:249]
	v_lshlrev_b32_e32 v250, 16, v224
	v_and_b32_e32 v251, 0xffff0000, v224
	v_pk_mul_f32 v[36:37], v[36:37], v[168:169] op_sel_hi:[1,0]
	v_pk_fma_f32 v[36:37], v[36:37], v[236:237], v[250:251]
	v_lshlrev_b32_e32 v252, 16, v225
	v_and_b32_e32 v253, 0xffff0000, v225
	v_pk_mul_f32 v[38:39], v[38:39], v[168:169] op_sel_hi:[1,0]
	v_pk_fma_f32 v[38:39], v[38:39], v[238:239], v[252:253]
	v_lshlrev_b32_e32 v248, 16, v226
	v_and_b32_e32 v249, 0xffff0000, v226
	v_pk_mul_f32 v[32:33], v[32:33], v[168:169] op_sel_hi:[1,0]
	v_pk_fma_f32 v[32:33], v[32:33], v[240:241], v[248:249]
	v_lshlrev_b32_e32 v250, 16, v227
	v_and_b32_e32 v251, 0xffff0000, v227
	v_pk_mul_f32 v[34:35], v[34:35], v[168:169] op_sel_hi:[1,0]
	v_pk_fma_f32 v[34:35], v[34:35], v[242:243], v[250:251]
	v_add_u32_e32 v161, 0x48000, v152
	v_lshlrev_b32_e32 v161, 1, v161
	global_store_dwordx4 v161, v[44:47], s[64:65]
	global_store_dwordx4 v161, v[40:43], s[64:65] offset:16
	global_store_dwordx4 v161, v[36:39], s[64:65] offset:512
	global_store_dwordx4 v161, v[32:35], s[64:65] offset:528
	s_waitcnt vmcnt(18)
; __device__ __forceinline__ float bf_lo(unsigned w) { return __uint_as_float(w << 16); }
; __device__ __forceinline__ float bf_hi(unsigned w) { return __uint_as_float(w & 0xffff0000u); }
; __device__ __forceinline__ unsigned pk2(float lo, float hi) { bf16x2_t r = __builtin_convertvector((f32x2_t){lo, hi}, bf16x2_t); return __builtin_bit_cast(unsigned, r); }
; template <bool SRC_F32, bool FINAL, int R> __device__ __forceinline__ void ew_compute(const EwSet<SRC_F32, R>& S, int rb, const f32x4 (&g)[4], bf16* hb_out, float* out32, float scale, float* rs_out, int lane) {
;     ...
;             f32x4 h;
;             if constexpr (SRC_F32) h = S.h32[i][j];
;             else { const v2u hw = S.hb[i][j]; h.x = bf_lo(hw.x); h.y = bf_hi(hw.x); h.z = bf_lo(hw.y); h.w = bf_hi(hw.y); }
;             const v2u fw = S.fw[i][j];
;             f32x4 v; v.x = h.x + bf_lo(fw.x) * rs * g[j].x; v.y = h.y + bf_hi(fw.x) * rs * g[j].y; v.z = h.z + bf_lo(fw.y) * rs * g[j].z; v.w = h.w + bf_hi(fw.y) * rs * g[j].w;
;             if (FINAL) __builtin_nontemporal_store(v, (f32x4*)(out32 + (size_t)(rb + i) * D) + lane + 64 * j);
;             else { v2u o; o.x = pk2(v.x, v.y); o.y = pk2(v.z, v.w); ((v2u*)(hb_out + (size_t)(rb + i) * D) + lane)[64 * j] = o; s2 += (v.x * v.x + v.y * v.y) + (v.z * v.z + v.w * v.w); }
	v_lshlrev_b32_e32 v248, 16, v178
	v_and_b32_e32 v249, 0xffff0000, v178
	v_pk_mul_f32 v[28:29], v[28:29], v[244:245] op_sel_hi:[1,0]
	v_pk_fma_f32 v[28:29], v[28:29], v[228:229], v[248:249]
	v_lshlrev_b32_e32 v250, 16, v179
	v_and_b32_e32 v251, 0xffff0000, v179
	v_pk_mul_f32 v[30:31], v[30:31], v[244:245] op_sel_hi:[1,0]
	v_pk_fma_f32 v[30:31], v[30:31], v[230:231], v[250:251]
	v_lshlrev_b32_e32 v252, 16, v180
	v_and_b32_e32 v253, 0xffff0000, v180
	v_pk_mul_f32 v[24:25], v[24:25], v[244:245] op_sel_hi:[1,0]
	v_pk_fma_f32 v[24:25], v[24:25], v[232:233], v[252:253]
	v_lshlrev_b32_e32 v248, 16, v181
	v_and_b32_e32 v249, 0xffff0000, v181
	v_pk_mul_f32 v[26:27], v[26:27], v[244:245] op_sel_hi:[1,0]
	v_pk_fma_f32 v[26:27], v[26:27], v[234:235], v[248:249]
	v_lshlrev_b32_e32 v250, 16, v182
	v_and_b32_e32 v251, 0xffff0000, v182
	v_pk_mul_f32 v[20:21], v[20:21], v[244:245] op_sel_hi:[1,0]
	v_pk_fma_f32 v[20:21], v[20:21], v[236:237], v[250:251]
	v_lshlrev_b32_e32 v252, 16, v183
	v_and_b32_e32 v253, 0xffff0000, v183
	v_pk_mul_f32 v[22:23], v[22:23], v[244:245] op_sel_hi:[1,0]
	v_pk_fma_f32 v[22:23], v[22:23], v[238:239], v[252:253]
	v_lshlrev_b32_e32 v248, 16, v184
	v_and_b32_e32 v249, 0xffff0000, v184
	v_pk_mul_f32 v[16:17], v[16:17], v[244:245] op_sel_hi:[1,0]
	v_pk_fma_f32 v[16:17], v[16:17], v[240:241], v[248:249]
	v_lshlrev_b32_e32 v250, 16, v185
	v_and_b32_e32 v251, 0xffff0000, v185
	v_pk_mul_f32 v[18:19], v[18:19], v[244:245] op_sel_hi:[1,0]
	v_pk_fma_f32 v[18:19], v[18:19], v[242:243], v[250:251]
	v_add_u32_e32 v161, 0x50000, v152
	v_lshlrev_b32_e32 v161, 1, v161
	global_store_dwordx4 v161, v[28:31], s[64:65]
	global_store_dwordx4 v161, v[24:27], s[64:65] offset:16
	global_store_dwordx4 v161, v[20:23], s[64:65] offset:512
	global_store_dwordx4 v161, v[16:19], s[64:65] offset:528
	s_waitcnt vmcnt(20)
	v_lshlrev_b32_e32 v248, 16, v186
	v_and_b32_e32 v249, 0xffff0000, v186
	v_pk_mul_f32 v[12:13], v[12:13], v[246:247] op_sel_hi:[1,0]
	v_pk_fma_f32 v[12:13], v[12:13], v[228:229], v[248:249]
	v_lshlrev_b32_e32 v250, 16, v187
	v_and_b32_e32 v251, 0xffff0000, v187
	v_pk_mul_f32 v[14:15], v[14:15], v[246:247] op_sel_hi:[1,0]
	v_pk_fma_f32 v[14:15], v[14:15], v[230:231], v[250:251]
	v_lshlrev_b32_e32 v252, 16, v188
	v_and_b32_e32 v253, 0xffff0000, v188
	v_pk_mul_f32 v[8:9], v[8:9], v[246:247] op_sel_hi:[1,0]
	v_pk_fma_f32 v[8:9], v[8:9], v[232:233], v[252:253]
	v_lshlrev_b32_e32 v248, 16, v189
	v_and_b32_e32 v249, 0xffff0000, v189
	v_pk_mul_f32 v[10:11], v[10:11], v[246:247] op_sel_hi:[1,0]
	v_pk_fma_f32 v[10:11], v[10:11], v[234:235], v[248:249]
	v_lshlrev_b32_e32 v250, 16, v190
	v_and_b32_e32 v251, 0xffff0000, v190
	v_pk_mul_f32 v[4:5], v[4:5], v[246:247] op_sel_hi:[1,0]
	v_pk_fma_f32 v[4:5], v[4:5], v[236:237], v[250:251]
	v_lshlrev_b32_e32 v252, 16, v191
	v_and_b32_e32 v253, 0xffff0000, v191
	v_pk_mul_f32 v[6:7], v[6:7], v[246:247] op_sel_hi:[1,0]
	v_pk_fma_f32 v[6:7], v[6:7], v[238:239], v[252:253]
	v_lshlrev_b32_e32 v248, 16, v192
	v_and_b32_e32 v249, 0xffff0000, v192
	v_pk_mul_f32 v[0:1], v[0:1], v[246:247] op_sel_hi:[1,0]
	v_pk_fma_f32 v[0:1], v[0:1], v[240:241], v[248:249]
	v_lshlrev_b32_e32 v250, 16, v193
	v_and_b32_e32 v251, 0xffff0000, v193
	v_pk_mul_f32 v[2:3], v[2:3], v[246:247] op_sel_hi:[1,0]
	v_pk_fma_f32 v[2:3], v[2:3], v[242:243], v[250:251]
	v_add_u32_e32 v161, 0x58000, v152
	v_lshlrev_b32_e32 v161, 1, v161
	global_store_dwordx4 v161, v[12:15], s[64:65]
	global_store_dwordx4 v161, v[8:11], s[64:65] offset:16
	global_store_dwordx4 v161, v[4:7], s[64:65] offset:512
	global_store_dwordx4 v161, v[0:3], s[64:65] offset:528
	s_and_b64 vcc, exec, s[4:5]
	s_mov_b64 s[4:5], -1
	s_cbranch_vccnz .LBB0_1376
	s_andn2_b64 vcc, exec, s[22:23]
	s_cbranch_vccnz .LBB0_1375
	s_barrier
	s_branch .LBB0_1375
